# SSD output phase: per-head loop rewritten by hand (batched prev-state fragment loads, fma/exp/mul decay terms without spilled lane masks, diagonal block fixed up separately), z-tile staging with 4 loa
# speedup vs baseline: 1.0168x; 1.0168x over previous
; #define LAS __attribute__((address_space(3)))
; __device__ __forceinline__ f32x16 mfma32(bf16x8 a, bf16x8 b, f32x16 c) { return __builtin_amdgcn_mfma_f32_32x32x16_bf16(a, b, c, 0, 0, 0); }
; __device__ __forceinline__ void phase_ssd_y(const PT& p, LAS unsigned char* lds, int tid, int lane, int wave) {
;     ...
; #pragma unroll 4
;         for (int i = 0; i < 16; ++i) { const int pid = tid + 512 * i, row = pid >> 6, c8 = pid & 63;
;             *(LAS u32x4*)(tile + row * SY_TP + 16 * c8) = *(const u32x4*)(Ycat + ((size_t)tok0 + row) * 4096 + 2048 + grp * 512 + 8 * c8); }
;         __syncthreads();
;         const int pb = wave >> 2, lb = wave & 3, l = lb * 32 + r32; const size_t tok = (size_t)tok0 + l;
;         bf16x8 cf[8];
; #pragma unroll
;         for (int st = 0; st < 8; ++st) cf[st] = ld_frag16(Cn + tok * 512 + grp * 128 + 16 * st + 8 * h);
;         f32x16 X[4];
; #pragma unroll
;         for (int sb = 0; sb < 4; ++sb) {
; #pragma unroll
;             for (int i = 0; i < 16; ++i) X[sb][i] = 0.f;
;             if (sb <= lb) {
; #pragma unroll
;                 for (int st = 0; st < 8; ++st) X[sb] = mfma32(ld_frag16(Bn + ((size_t)tok0 + sb * 32 + r32) * 512 + grp * 128 + 16 * st + 8 * h), cf[st], X[sb]);
;             }
;         }
.LBB0_485:
	v_add_u32_e32 v6, s80, v117
	v_ashrrev_i32_e32 v32, 6, v6
	v_ashrrev_i32_e32 v33, 31, v32
	v_lshl_add_u64 v[24:25], v[32:33], 0, s[92:93]
	v_lshlrev_b64 v[24:25], 13, v[24:25]
	v_lshl_add_u64 v[24:25], s[88:89], 0, v[24:25]
	s_lshl_b32 s96, s1, 1
	v_lshl_add_u64 v[24:25], v[24:25], 0, s[96:97]
	v_lshl_add_u64 v[24:25], v[24:25], 0, v[120:121]
	v_add_co_u32_e32 v24, vcc, 0x1000, v24
	v_mad_u64_u32 v[32:33], s[82:83], v32, s33, v[122:123]
	s_nop 0
	v_addc_co_u32_e32 v25, vcc, 0, v25, vcc
	global_load_dwordx4 v[40:43], v[24:25], off
	s_addk_i32 s80, 0x800
	s_cmpk_eq_i32 s80, 0x2000
	v_add_u32_e32 v26, 0x200, v6
	v_ashrrev_i32_e32 v34, 6, v26
	v_ashrrev_i32_e32 v35, 31, v34
	v_lshl_add_u64 v[26:27], v[34:35], 0, s[92:93]
	v_lshlrev_b64 v[26:27], 13, v[26:27]
	v_lshl_add_u64 v[26:27], s[88:89], 0, v[26:27]
	v_lshl_add_u64 v[26:27], v[26:27], 0, s[96:97]
	v_lshl_add_u64 v[26:27], v[26:27], 0, v[120:121]
	v_add_co_u32_e32 v26, vcc, s0, v26
	v_mad_u64_u32 v[34:35], s[82:83], v34, s33, v[122:123]
	s_nop 0
	v_addc_co_u32_e32 v27, vcc, 0, v27, vcc
	global_load_dwordx4 v[44:47], v[26:27], off
	v_add_u32_e32 v28, 0x400, v6
	v_ashrrev_i32_e32 v36, 6, v28
	v_ashrrev_i32_e32 v37, 31, v36
	v_lshl_add_u64 v[28:29], v[36:37], 0, s[92:93]
	v_lshlrev_b64 v[28:29], 13, v[28:29]
	v_lshl_add_u64 v[28:29], s[88:89], 0, v[28:29]
	v_lshl_add_u64 v[28:29], v[28:29], 0, s[96:97]
	v_lshl_add_u64 v[28:29], v[28:29], 0, v[120:121]
	v_add_co_u32_e32 v28, vcc, s0, v28
	v_mad_u64_u32 v[36:37], s[82:83], v36, s33, v[122:123]
	s_nop 0
	v_addc_co_u32_e32 v29, vcc, 0, v29, vcc
	global_load_dwordx4 v[48:51], v[28:29], off
	v_add_u32_e32 v30, 0x600, v6
	v_ashrrev_i32_e32 v38, 6, v30
	v_ashrrev_i32_e32 v39, 31, v38
	v_lshl_add_u64 v[30:31], v[38:39], 0, s[92:93]
	v_lshlrev_b64 v[30:31], 13, v[30:31]
	v_lshl_add_u64 v[30:31], s[88:89], 0, v[30:31]
	v_lshl_add_u64 v[30:31], v[30:31], 0, s[96:97]
	v_lshl_add_u64 v[30:31], v[30:31], 0, v[120:121]
	v_add_co_u32_e32 v30, vcc, 0x1000, v30
	v_mad_u64_u32 v[38:39], s[82:83], v38, s33, v[122:123]
	s_nop 0
	v_addc_co_u32_e32 v31, vcc, 0, v31, vcc
	global_load_dwordx4 v[52:55], v[30:31], off
	s_waitcnt vmcnt(3)
	ds_write_b128 v32, v[40:43] offset:9728
	s_waitcnt vmcnt(2)
	ds_write_b128 v34, v[44:47] offset:9728
	s_waitcnt vmcnt(1)
	ds_write_b128 v36, v[48:51] offset:9728
	s_waitcnt vmcnt(0)
	ds_write_b128 v38, v[52:55] offset:9728
	s_cbranch_scc0 .LBB0_485
	v_mov_b32_e32 v1, s93
	v_or_b32_e32 v0, s92, v124
	v_readlane_b32 s80, v249, 16
	v_lshlrev_b64 v[0:1], 10, v[0:1]
	v_readlane_b32 s81, v249, 17
	s_lshl_b32 s96, s3, 8
	v_mov_b32_e32 v141, v121
	v_lshl_add_u64 v[0:1], s[80:81], 0, v[0:1]
	v_lshl_add_u64 v[0:1], v[0:1], 0, s[96:97]
	v_lshl_add_u64 v[0:1], v[0:1], 0, v[140:141]
	s_waitcnt lgkmcnt(0)
	s_barrier
	global_load_dwordx4 v[80:83], v[0:1], off
	global_load_dwordx4 v[84:87], v[0:1], off offset:32
	global_load_dwordx4 v[88:91], v[0:1], off offset:64
	global_load_dwordx4 v[92:95], v[0:1], off offset:96
	global_load_dwordx4 v[96:99], v[0:1], off offset:128
	global_load_dwordx4 v[100:103], v[0:1], off offset:160
	global_load_dwordx4 v[104:107], v[0:1], off offset:192
	global_load_dwordx4 v[108:111], v[0:1], off offset:224
	v_mov_b32_e32 v1, s93
	v_or_b32_e32 v0, s92, v116
	v_lshl_add_u64 v[64:65], v[128:129], 0, s[96:97]
	v_lshlrev_b64 v[0:1], 10, v[0:1]
	v_lshl_add_u64 v[20:21], v[64:65], 0, v[0:1]
	global_load_dwordx4 v[0:3], v[20:21], off
	global_load_dwordx4 v[212:215], v[20:21], off offset:32
	global_load_dwordx4 v[216:219], v[20:21], off offset:64
	global_load_dwordx4 v[220:223], v[20:21], off offset:96
	global_load_dwordx4 v[224:227], v[20:21], off offset:128
	global_load_dwordx4 v[228:231], v[20:21], off offset:160
	global_load_dwordx4 v[232:235], v[20:21], off offset:192
	global_load_dwordx4 v[236:239], v[20:21], off offset:224
	s_and_b64 vcc, exec, s[90:91]
	s_waitcnt vmcnt(7)
	v_mfma_f32_32x32x16_bf16 v[0:15], v[0:3], v[80:83], 0
	s_waitcnt vmcnt(6)
	v_mfma_f32_32x32x16_bf16 v[0:15], v[212:215], v[84:87], v[0:15]
	s_waitcnt vmcnt(5)
	v_mfma_f32_32x32x16_bf16 v[0:15], v[216:219], v[88:91], v[0:15]
	s_waitcnt vmcnt(4)
	v_mfma_f32_32x32x16_bf16 v[0:15], v[220:223], v[92:95], v[0:15]
	s_waitcnt vmcnt(3)
	v_mfma_f32_32x32x16_bf16 v[0:15], v[224:227], v[96:99], v[0:15]
	s_waitcnt vmcnt(2)
	v_mfma_f32_32x32x16_bf16 v[0:15], v[228:231], v[100:103], v[0:15]
	s_waitcnt vmcnt(1)
	v_mfma_f32_32x32x16_bf16 v[0:15], v[232:235], v[104:107], v[0:15]
	s_waitcnt vmcnt(0)
	v_mfma_f32_32x32x16_bf16 v[0:15], v[236:239], v[108:111], v[0:15]
	s_cbranch_vccz .LBB0_488
	v_mov_b32_e32 v17, s93
	v_or_b32_e32 v16, s92, v130
	v_lshlrev_b64 v[16:17], 10, v[16:17]
	v_lshl_add_u64 v[36:37], v[64:65], 0, v[16:17]
	global_load_dwordx4 v[16:19], v[36:37], off
	global_load_dwordx4 v[212:215], v[36:37], off offset:32
	global_load_dwordx4 v[216:219], v[36:37], off offset:64
	global_load_dwordx4 v[220:223], v[36:37], off offset:96
	global_load_dwordx4 v[224:227], v[36:37], off offset:128
	global_load_dwordx4 v[228:231], v[36:37], off offset:160
	global_load_dwordx4 v[232:235], v[36:37], off offset:192
	global_load_dwordx4 v[236:239], v[36:37], off offset:224
	s_waitcnt vmcnt(7)
	v_mfma_f32_32x32x16_bf16 v[16:31], v[16:19], v[80:83], 0
	s_waitcnt vmcnt(6)
	v_mfma_f32_32x32x16_bf16 v[16:31], v[212:215], v[84:87], v[16:31]
	s_waitcnt vmcnt(5)
	v_mfma_f32_32x32x16_bf16 v[16:31], v[216:219], v[88:91], v[16:31]
	s_waitcnt vmcnt(4)
	v_mfma_f32_32x32x16_bf16 v[16:31], v[220:223], v[92:95], v[16:31]
	s_waitcnt vmcnt(3)
	v_mfma_f32_32x32x16_bf16 v[16:31], v[224:227], v[96:99], v[16:31]
	s_waitcnt vmcnt(2)
	v_mfma_f32_32x32x16_bf16 v[16:31], v[228:231], v[100:103], v[16:31]
	s_waitcnt vmcnt(1)
	v_mfma_f32_32x32x16_bf16 v[16:31], v[232:235], v[104:107], v[16:31]
	s_waitcnt vmcnt(0)
	v_mfma_f32_32x32x16_bf16 v[16:31], v[236:239], v[108:111], v[16:31]
	s_branch .LBB0_489

; __device__ __forceinline__ f32x16 mfma32(bf16x8 a, bf16x8 b, f32x16 c) { return __builtin_amdgcn_mfma_f32_32x32x16_bf16(a, b, c, 0, 0, 0); }
; __device__ __forceinline__ void phase_ssd_y(const PT& p, LAS unsigned char* lds, int tid, int lane, int wave) {
;     ...
;         for (int sb = 0; sb < 4; ++sb) {
; #pragma unroll
;             for (int i = 0; i < 16; ++i) X[sb][i] = 0.f;
;             if (sb <= lb) {
; #pragma unroll
;                 for (int st = 0; st < 8; ++st) X[sb] = mfma32(ld_frag16(Bn + ((size_t)tok0 + sb * 32 + r32) * 512 + grp * 128 + 16 * st + 8 * h), cf[st], X[sb]);
;             }
;         }
.LBB0_489:
	v_readlane_b32 s82, v249, 33
	v_readlane_b32 s83, v249, 34
	v_mov_b32_e32 v32, 0
	s_andn2_b64 vcc, exec, s[82:83]
	v_cndmask_b32_e64 v33, 0, 1, s[82:83]
	v_cmp_ne_u32_e64 s[80:81], 1, v33
	v_mov_b32_e32 v48, 0
	v_mov_b32_e32 v49, 0
	v_mov_b32_e32 v50, 0
	v_mov_b32_e32 v51, 0
	v_mov_b32_e32 v52, 0
	v_mov_b32_e32 v53, 0
	v_mov_b32_e32 v54, 0
	v_mov_b32_e32 v55, 0
	v_mov_b32_e32 v56, 0
	v_mov_b32_e32 v57, 0
	v_mov_b32_e32 v58, 0
	v_mov_b32_e32 v59, 0
	v_mov_b32_e32 v60, 0
	v_mov_b32_e32 v61, 0
	v_mov_b32_e32 v62, 0
	v_mov_b32_e32 v63, 0
	s_cbranch_vccnz .LBB0_491
	v_mov_b32_e32 v35, s93
	v_or_b32_e32 v34, s92, v132
	v_lshlrev_b64 v[34:35], 10, v[34:35]
	v_lshl_add_u64 v[38:39], v[64:65], 0, v[34:35]
	global_load_dwordx4 v[34:37], v[38:39], off
	global_load_dwordx4 v[212:215], v[38:39], off offset:32
	global_load_dwordx4 v[216:219], v[38:39], off offset:64
	global_load_dwordx4 v[220:223], v[38:39], off offset:96
	global_load_dwordx4 v[224:227], v[38:39], off offset:128
	global_load_dwordx4 v[228:231], v[38:39], off offset:160
	global_load_dwordx4 v[232:235], v[38:39], off offset:192
	global_load_dwordx4 v[236:239], v[38:39], off offset:224
	s_waitcnt vmcnt(7)
	v_mfma_f32_32x32x16_bf16 v[48:63], v[34:37], v[80:83], 0
	s_waitcnt vmcnt(6)
	v_mfma_f32_32x32x16_bf16 v[48:63], v[212:215], v[84:87], v[48:63]
	s_waitcnt vmcnt(5)
	v_mfma_f32_32x32x16_bf16 v[48:63], v[216:219], v[88:91], v[48:63]
	s_waitcnt vmcnt(4)
	v_mfma_f32_32x32x16_bf16 v[48:63], v[220:223], v[92:95], v[48:63]
	s_waitcnt vmcnt(3)
	v_mfma_f32_32x32x16_bf16 v[48:63], v[224:227], v[96:99], v[48:63]
	s_waitcnt vmcnt(2)
	v_mfma_f32_32x32x16_bf16 v[48:63], v[228:231], v[100:103], v[48:63]
	s_waitcnt vmcnt(1)
	v_mfma_f32_32x32x16_bf16 v[48:63], v[232:235], v[104:107], v[48:63]
	s_waitcnt vmcnt(0)
	v_mfma_f32_32x32x16_bf16 v[48:63], v[236:239], v[108:111], v[48:63]
.LBB0_491:
	v_readlane_b32 s84, v249, 35
	v_readlane_b32 s85, v249, 36
	s_andn2_b64 vcc, exec, s[84:85]
	v_mov_b32_e32 v34, 0
	v_cndmask_b32_e64 v33, 0, 1, s[84:85]
	v_cmp_ne_u32_e64 s[82:83], 1, v33
	v_mov_b32_e32 v33, 0
	v_mov_b32_e32 v35, 0
	v_mov_b32_e32 v36, 0
	v_mov_b32_e32 v37, 0
	v_mov_b32_e32 v38, 0
	v_mov_b32_e32 v39, 0
	v_mov_b32_e32 v40, 0
	v_mov_b32_e32 v41, 0
	v_mov_b32_e32 v42, 0
	v_mov_b32_e32 v43, 0
	v_mov_b32_e32 v44, 0
	v_mov_b32_e32 v45, 0
	v_mov_b32_e32 v46, 0
	v_mov_b32_e32 v47, 0
	s_cbranch_vccnz .LBB0_493
	v_mov_b32_e32 v33, s93
	v_or_b32_e32 v32, s92, v134
	v_lshlrev_b64 v[32:33], 10, v[32:33]
	v_lshl_add_u64 v[68:69], v[64:65], 0, v[32:33]
	global_load_dwordx4 v[32:35], v[68:69], off
	global_load_dwordx4 v[212:215], v[68:69], off offset:32
	global_load_dwordx4 v[216:219], v[68:69], off offset:64
	global_load_dwordx4 v[220:223], v[68:69], off offset:96
	global_load_dwordx4 v[224:227], v[68:69], off offset:128
	global_load_dwordx4 v[228:231], v[68:69], off offset:160
	global_load_dwordx4 v[232:235], v[68:69], off offset:192
	global_load_dwordx4 v[236:239], v[68:69], off offset:224
	s_waitcnt vmcnt(7)
	v_mfma_f32_32x32x16_bf16 v[32:47], v[32:35], v[80:83], 0
	s_waitcnt vmcnt(6)
	v_mfma_f32_32x32x16_bf16 v[32:47], v[212:215], v[84:87], v[32:47]
	s_waitcnt vmcnt(5)
	v_mfma_f32_32x32x16_bf16 v[32:47], v[216:219], v[88:91], v[32:47]
	s_waitcnt vmcnt(4)
	v_mfma_f32_32x32x16_bf16 v[32:47], v[220:223], v[92:95], v[32:47]
	s_waitcnt vmcnt(3)
	v_mfma_f32_32x32x16_bf16 v[32:47], v[224:227], v[96:99], v[32:47]
	s_waitcnt vmcnt(2)
	v_mfma_f32_32x32x16_bf16 v[32:47], v[228:231], v[100:103], v[32:47]
	s_waitcnt vmcnt(1)
	v_mfma_f32_32x32x16_bf16 v[32:47], v[232:235], v[104:107], v[32:47]
	s_waitcnt vmcnt(0)
	v_mfma_f32_32x32x16_bf16 v[32:47], v[236:239], v[108:111], v[32:47]

; #define LAS __attribute__((address_space(3)))
; __device__ __forceinline__ f32x16 mfma32(bf16x8 a, bf16x8 b, f32x16 c) { return __builtin_amdgcn_mfma_f32_32x32x16_bf16(a, b, c, 0, 0, 0); }
; __device__ __forceinline__ void phase_ssd_y(const PT& p, LAS unsigned char* lds, int tid, int lane, int wave) {
;     ...
;         for (int r = 0; r < 8; ++r) {
;             const int hh = grp * 8 + r;
;             f32x16 acc;
; #pragma unroll
;             for (int i = 0; i < 16; ++i) acc[i] = 0.f;
;             const bf16* pp = PV + ((size_t)(bc * 32 + hh) * 64 + pb * 32 + r32) * 128 + 8 * h;
; #pragma unroll
;             for (int st = 0; st < 8; ++st) acc = mfma32(ld_frag16(pp + 16 * st), cf[st], acc);
;             const float al = acum[r * 128 + l]; const float el = __expf(al); const float dsk = p.in[11][hh];
; #pragma unroll
;             for (int i = 0; i < 16; ++i) acc[i] *= el;
;             const bf16* xrow = xT + ((size_t)bc * 2048 + hh * 64 + pb * 32 + r32) * 128 + 4 * h;
; #pragma unroll
;             for (int sb = 0; sb < 4; ++sb) {
;                 if (sb <= lb) {
;                     f32x16 mm;
; #pragma unroll
;                     for (int qd = 0; qd < 4; ++qd) {
;                         const int s0 = sb * 32 + 8 * qd + 4 * h;
;                         const f32x4 as = *(const LAS f32x4*)(acum + r * 128 + s0), ds = *(const LAS f32x4*)(dtt + r * 128 + s0);
; #pragma unroll
;                         for (int j = 0; j < 4; ++j) { const float v = X[sb][4 * qd + j] * __expf(al - as[j]) * ds[j]; mm[4 * qd + j] = (s0 + j < l) ? v : ((s0 + j == l) ? v + dsk : 0.f); }
.LBB0_495:
	v_readfirstlane_b32 s98, v117
	v_bfe_u32 v164, v117, 5, 1
	s_nop 3
	s_bfe_u32 s98, s98, 0x20006
	v_bfe_u32 v165, v117, 8, 1
	v_mov_b32_e32 v163, 0xbfb8aa3b
	v_lshlrev_b32_e32 v244, 2, v164
	v_sub_u32_e32 v160, v116, v244
	v_lshlrev_b32_e32 v161, 4, v164
	v_lshlrev_b32_e32 v141, 2, v124
	v_mul_u32_u24_e32 v162, 0x410, v124
	v_lshlrev_b32_e32 v245, 6, v165
	v_lshlrev_b32_e32 v244, 3, v164
	v_add3_u32 v162, v162, v245, v244
	v_add_u32_e32 v162, 0x2600, v162
	ds_read_b64 v[112:113], v188
	s_waitcnt lgkmcnt(0)
	v_readfirstlane_b32 s84, v112
	v_readfirstlane_b32 s85, v113
	s_nop 3
	s_add_u32 s84, s84, s2
	s_addc_u32 s85, s85, s3
	s_mov_b32 s2, 0
.Lp5_head:
	v_lshl_add_u64 v[204:205], v[142:143], 0, s[94:95]
	v_lshl_add_u64 v[206:207], v[144:145], 0, s[94:95]
	v_mov_b32_e32 v164, 0
	global_load_dword v159, v164, s[84:85]
	global_load_dwordx4 v[64:67], v[204:205], off
	global_load_dwordx4 v[112:115], v[204:205], off offset:32
	global_load_dwordx4 v[212:215], v[204:205], off offset:64
	global_load_dwordx4 v[216:219], v[204:205], off offset:96
	global_load_dwordx4 v[220:223], v[204:205], off offset:128
	global_load_dwordx4 v[224:227], v[204:205], off offset:160
	global_load_dwordx4 v[228:231], v[204:205], off offset:192
	global_load_dwordx4 v[232:235], v[204:205], off offset:224
	v_add_co_u32_e32 v206, vcc, 0x1a900000, v206
	s_nop 1
	v_addc_co_u32_e32 v207, vcc, 0, v207, vcc
	global_load_dwordx2 v[150:151], v[206:207], off offset:0
	global_load_dwordx2 v[152:153], v[206:207], off offset:16
	global_load_dwordx2 v[154:155], v[206:207], off offset:32
	global_load_dwordx2 v[156:157], v[206:207], off offset:48
	global_load_dwordx2 v[192:193], v[206:207], off offset:64
	global_load_dwordx2 v[194:195], v[206:207], off offset:80
	global_load_dwordx2 v[198:199], v[206:207], off offset:96
	global_load_dwordx2 v[200:201], v[206:207], off offset:112
	ds_read_b32 v158, v141
	s_waitcnt vmcnt(15)
	v_mfma_f32_32x32x16_bf16 v[64:79], v[64:67], v[80:83], 0
	s_waitcnt vmcnt(14)
	v_mfma_f32_32x32x16_bf16 v[64:79], v[112:115], v[84:87], v[64:79]
	s_waitcnt vmcnt(13)
	v_mfma_f32_32x32x16_bf16 v[64:79], v[212:215], v[88:91], v[64:79]
	s_waitcnt vmcnt(12)
	v_mfma_f32_32x32x16_bf16 v[64:79], v[216:219], v[92:95], v[64:79]
	s_waitcnt vmcnt(11)
	v_mfma_f32_32x32x16_bf16 v[64:79], v[220:223], v[96:99], v[64:79]
	s_waitcnt vmcnt(10)
	v_mfma_f32_32x32x16_bf16 v[64:79], v[224:227], v[100:103], v[64:79]
	s_waitcnt vmcnt(9)
	v_mfma_f32_32x32x16_bf16 v[64:79], v[228:231], v[104:107], v[64:79]
	s_waitcnt vmcnt(8)
	v_mfma_f32_32x32x16_bf16 v[64:79], v[232:235], v[108:111], v[64:79]
	s_waitcnt lgkmcnt(0)
	v_mul_f32_e32 v164, 0x3fb8aa3b, v158
	v_exp_f32_e32 v165, v164
	v_mov_b32_e32 v158, v164
	s_nop 8
	v_mul_f32_e32 v64, v165, v64
	v_mul_f32_e32 v65, v165, v65
	v_mul_f32_e32 v66, v165, v66
	v_mul_f32_e32 v67, v165, v67
	v_mul_f32_e32 v68, v165, v68
	v_mul_f32_e32 v69, v165, v69
	v_mul_f32_e32 v70, v165, v70
	v_mul_f32_e32 v71, v165, v71
	v_mul_f32_e32 v72, v165, v72
	v_mul_f32_e32 v73, v165, v73
	v_mul_f32_e32 v74, v165, v74
	v_mul_f32_e32 v75, v165, v75
	v_mul_f32_e32 v76, v165, v76
	v_mul_f32_e32 v77, v165, v77
	v_mul_f32_e32 v78, v165, v78
	v_mul_f32_e32 v79, v165, v79
	ds_read_b128 v[236:239], v161 offset:0
	ds_read_b128 v[240:243], v161 offset:4096
	ds_read_b128 v[250:253], v161 offset:32
	ds_read_b128 v[146:149], v161 offset:4128
	global_load_dwordx2 v[112:113], v[206:207], off offset:128
	global_load_dwordx2 v[114:115], v[206:207], off offset:144
	global_load_dwordx2 v[202:203], v[206:207], off offset:160
	global_load_dwordx2 v[204:205], v[206:207], off offset:176
	s_waitcnt lgkmcnt(2)
	v_fma_f32 v164, v236, v163, v158
	v_fma_f32 v165, v237, v163, v158
	v_fma_f32 v244, v238, v163, v158
	v_fma_f32 v245, v239, v163, v158
	v_exp_f32_e32 v164, v164
	v_exp_f32_e32 v165, v165
	v_exp_f32_e32 v244, v244
	v_exp_f32_e32 v245, v245
	v_mul_f32_e32 v164, v164, v240
	v_mul_f32_e32 v165, v165, v241
	v_mul_f32_e32 v244, v244, v242
	v_mul_f32_e32 v245, v245, v243
	ds_read_b128 v[236:239], v161 offset:64
	ds_read_b128 v[240:243], v161 offset:4160
	v_mul_f32_e32 v212, v0, v164
	v_mul_f32_e32 v213, v1, v165
	v_mul_f32_e32 v214, v2, v244
	v_mul_f32_e32 v215, v3, v245
	s_waitcnt lgkmcnt(2)
	v_fma_f32 v164, v250, v163, v158
	v_fma_f32 v165, v251, v163, v158
	v_fma_f32 v244, v252, v163, v158
	v_fma_f32 v245, v253, v163, v158
	v_exp_f32_e32 v164, v164
	v_exp_f32_e32 v165, v165
	v_exp_f32_e32 v244, v244
	v_exp_f32_e32 v245, v245
	v_mul_f32_e32 v164, v164, v146
	v_mul_f32_e32 v165, v165, v147
	v_mul_f32_e32 v244, v244, v148
	v_mul_f32_e32 v245, v245, v149
	ds_read_b128 v[250:253], v161 offset:96
	ds_read_b128 v[146:149], v161 offset:4192
	v_mul_f32_e32 v216, v4, v164
	v_mul_f32_e32 v217, v5, v165
	v_mul_f32_e32 v218, v6, v244
	v_mul_f32_e32 v219, v7, v245
	s_waitcnt lgkmcnt(2)
	v_fma_f32 v164, v236, v163, v158
	v_fma_f32 v165, v237, v163, v158
	v_fma_f32 v244, v238, v163, v158
	v_fma_f32 v245, v239, v163, v158
	v_exp_f32_e32 v164, v164
	v_exp_f32_e32 v165, v165
	v_exp_f32_e32 v244, v244
	v_exp_f32_e32 v245, v245
	v_mul_f32_e32 v164, v164, v240
	v_mul_f32_e32 v165, v165, v241
	v_mul_f32_e32 v244, v244, v242
	v_mul_f32_e32 v245, v245, v243
	v_mul_f32_e32 v220, v8, v164
	v_mul_f32_e32 v221, v9, v165
	v_mul_f32_e32 v222, v10, v244
	v_mul_f32_e32 v223, v11, v245
	s_waitcnt lgkmcnt(0)
	v_fma_f32 v164, v250, v163, v158
	v_fma_f32 v165, v251, v163, v158
	v_fma_f32 v244, v252, v163, v158
	v_fma_f32 v245, v253, v163, v158
	v_exp_f32_e32 v164, v164
	v_exp_f32_e32 v165, v165
	v_exp_f32_e32 v244, v244
	v_exp_f32_e32 v245, v245
	v_mul_f32_e32 v164, v164, v146
	v_mul_f32_e32 v165, v165, v147
	v_mul_f32_e32 v244, v244, v148
	v_mul_f32_e32 v245, v245, v149
	v_mul_f32_e32 v224, v12, v164
	v_mul_f32_e32 v225, v13, v165
	v_mul_f32_e32 v226, v14, v244
	v_mul_f32_e32 v227, v15, v245
	s_cmp_lg_u32 s98, 0
	s_cbranch_scc1 .Lp5_nodiag0
; #define LAS __attribute__((address_space(3)))
; __device__ __forceinline__ f32x16 mfma32(bf16x8 a, bf16x8 b, f32x16 c) { return __builtin_amdgcn_mfma_f32_32x32x16_bf16(a, b, c, 0, 0, 0); }
; __device__ __forceinline__ void phase_ssd_y(const PT& p, LAS unsigned char* lds, int tid, int lane, int wave) {
;     ...
;                 if (sb <= lb) {
;                     f32x16 mm;
; #pragma unroll
;                     for (int qd = 0; qd < 4; ++qd) {
;                         const int s0 = sb * 32 + 8 * qd + 4 * h;
;                         const f32x4 as = *(const LAS f32x4*)(acum + r * 128 + s0), ds = *(const LAS f32x4*)(dtt + r * 128 + s0);
; #pragma unroll
;                         for (int j = 0; j < 4; ++j) { const float v = X[sb][4 * qd + j] * __expf(al - as[j]) * ds[j]; mm[4 * qd + j] = (s0 + j < l) ? v : ((s0 + j == l) ? v + dsk : 0.f); }
;                     }
; #pragma unroll
;                     for (int s2 = 0; s2 < 2; ++s2) acc = mfma32(ld_frag8x2(xrow + sb * 32 + 16 * s2), pack_frag(mm, s2), acc);
	v_add_f32_e32 v208, v212, v159
	v_add_f32_e32 v209, v213, v159
	v_cmp_eq_u32_e32 vcc, 0, v160
	v_cmp_eq_u32_e64 s[100:101], 1, v160
	s_nop 0
	v_cndmask_b32_e32 v208, 0, v208, vcc
	v_cndmask_b32_e64 v209, 0, v209, s[100:101]
	v_cmp_lt_i32_e32 vcc, 0, v160
	v_cmp_lt_i32_e64 s[100:101], 1, v160
	s_nop 0
	v_cndmask_b32_e32 v212, v208, v212, vcc
	v_cndmask_b32_e64 v213, v209, v213, s[100:101]
	v_add_f32_e32 v208, v214, v159
	v_add_f32_e32 v209, v215, v159
	v_cmp_eq_u32_e32 vcc, 2, v160
	v_cmp_eq_u32_e64 s[100:101], 3, v160
	s_nop 0
	v_cndmask_b32_e32 v208, 0, v208, vcc
	v_cndmask_b32_e64 v209, 0, v209, s[100:101]
	v_cmp_lt_i32_e32 vcc, 2, v160
	v_cmp_lt_i32_e64 s[100:101], 3, v160
	s_nop 0
	v_cndmask_b32_e32 v214, v208, v214, vcc
	v_cndmask_b32_e64 v215, v209, v215, s[100:101]
	v_add_f32_e32 v208, v216, v159
	v_add_f32_e32 v209, v217, v159
	v_cmp_eq_u32_e32 vcc, 8, v160
	v_cmp_eq_u32_e64 s[100:101], 9, v160
	s_nop 0
	v_cndmask_b32_e32 v208, 0, v208, vcc
	v_cndmask_b32_e64 v209, 0, v209, s[100:101]
	v_cmp_lt_i32_e32 vcc, 8, v160
	v_cmp_lt_i32_e64 s[100:101], 9, v160
	s_nop 0
	v_cndmask_b32_e32 v216, v208, v216, vcc
	v_cndmask_b32_e64 v217, v209, v217, s[100:101]
	v_add_f32_e32 v208, v218, v159
	v_add_f32_e32 v209, v219, v159
	v_cmp_eq_u32_e32 vcc, 10, v160
	v_cmp_eq_u32_e64 s[100:101], 11, v160
	s_nop 0
	v_cndmask_b32_e32 v208, 0, v208, vcc
	v_cndmask_b32_e64 v209, 0, v209, s[100:101]
	v_cmp_lt_i32_e32 vcc, 10, v160
	v_cmp_lt_i32_e64 s[100:101], 11, v160
	s_nop 0
	v_cndmask_b32_e32 v218, v208, v218, vcc
	v_cndmask_b32_e64 v219, v209, v219, s[100:101]
	v_add_f32_e32 v208, v220, v159
	v_add_f32_e32 v209, v221, v159
	v_cmp_eq_u32_e32 vcc, 16, v160
	v_cmp_eq_u32_e64 s[100:101], 17, v160
	s_nop 0
	v_cndmask_b32_e32 v208, 0, v208, vcc
	v_cndmask_b32_e64 v209, 0, v209, s[100:101]
	v_cmp_lt_i32_e32 vcc, 16, v160
	v_cmp_lt_i32_e64 s[100:101], 17, v160
	s_nop 0
	v_cndmask_b32_e32 v220, v208, v220, vcc
	v_cndmask_b32_e64 v221, v209, v221, s[100:101]
	v_add_f32_e32 v208, v222, v159
	v_add_f32_e32 v209, v223, v159
	v_cmp_eq_u32_e32 vcc, 18, v160
	v_cmp_eq_u32_e64 s[100:101], 19, v160
	s_nop 0
	v_cndmask_b32_e32 v208, 0, v208, vcc
	v_cndmask_b32_e64 v209, 0, v209, s[100:101]
	v_cmp_lt_i32_e32 vcc, 18, v160
	v_cmp_lt_i32_e64 s[100:101], 19, v160
	s_nop 0
	v_cndmask_b32_e32 v222, v208, v222, vcc
	v_cndmask_b32_e64 v223, v209, v223, s[100:101]
	v_add_f32_e32 v208, v224, v159
	v_add_f32_e32 v209, v225, v159
	v_cmp_eq_u32_e32 vcc, 24, v160
	v_cmp_eq_u32_e64 s[100:101], 25, v160
	s_nop 0
	v_cndmask_b32_e32 v208, 0, v208, vcc
	v_cndmask_b32_e64 v209, 0, v209, s[100:101]
	v_cmp_lt_i32_e32 vcc, 24, v160
	v_cmp_lt_i32_e64 s[100:101], 25, v160
	s_nop 0
	v_cndmask_b32_e32 v224, v208, v224, vcc
	v_cndmask_b32_e64 v225, v209, v225, s[100:101]
	v_add_f32_e32 v208, v226, v159
	v_add_f32_e32 v209, v227, v159
	v_cmp_eq_u32_e32 vcc, 26, v160
	v_cmp_eq_u32_e64 s[100:101], 27, v160
	s_nop 0
	v_cndmask_b32_e32 v208, 0, v208, vcc
	v_cndmask_b32_e64 v209, 0, v209, s[100:101]
	v_cmp_lt_i32_e32 vcc, 26, v160
	v_cmp_lt_i32_e64 s[100:101], 27, v160
	s_nop 0
	v_cndmask_b32_e32 v226, v208, v226, vcc
	v_cndmask_b32_e64 v227, v209, v227, s[100:101]
.Lp5_nodiag0:
	v_cvt_pk_bf16_f32 v228, v212, v213
	v_cvt_pk_bf16_f32 v229, v214, v215
	v_cvt_pk_bf16_f32 v230, v216, v217
	v_cvt_pk_bf16_f32 v231, v218, v219
	v_cvt_pk_bf16_f32 v232, v220, v221
	v_cvt_pk_bf16_f32 v233, v222, v223
	v_cvt_pk_bf16_f32 v234, v224, v225
	v_cvt_pk_bf16_f32 v235, v226, v227
	s_nop 0
	s_waitcnt vmcnt(8)
	v_mfma_f32_32x32x16_bf16 v[64:79], v[150:153], v[228:231], v[64:79]
	v_mfma_f32_32x32x16_bf16 v[64:79], v[154:157], v[232:235], v[64:79]
	s_cmp_lt_u32 s98, 1
	s_cbranch_scc1 .Lp5_gate
	ds_read_b128 v[236:239], v161 offset:128
	ds_read_b128 v[240:243], v161 offset:4224
	ds_read_b128 v[250:253], v161 offset:160
	ds_read_b128 v[146:149], v161 offset:4256
	global_load_dwordx2 v[150:151], v[206:207], off offset:192
	global_load_dwordx2 v[152:153], v[206:207], off offset:208
	global_load_dwordx2 v[154:155], v[206:207], off offset:224
	global_load_dwordx2 v[156:157], v[206:207], off offset:240
	s_waitcnt lgkmcnt(2)
	v_fma_f32 v164, v236, v163, v158
	v_fma_f32 v165, v237, v163, v158
	v_fma_f32 v244, v238, v163, v158
	v_fma_f32 v245, v239, v163, v158
	v_exp_f32_e32 v164, v164
	v_exp_f32_e32 v165, v165
	v_exp_f32_e32 v244, v244
	v_exp_f32_e32 v245, v245
	v_mul_f32_e32 v164, v164, v240
	v_mul_f32_e32 v165, v165, v241
	v_mul_f32_e32 v244, v244, v242
	v_mul_f32_e32 v245, v245, v243
	ds_read_b128 v[236:239], v161 offset:192
	ds_read_b128 v[240:243], v161 offset:4288
	v_mul_f32_e32 v212, v16, v164
	v_mul_f32_e32 v213, v17, v165
	v_mul_f32_e32 v214, v18, v244
	v_mul_f32_e32 v215, v19, v245
	s_waitcnt lgkmcnt(2)
	v_fma_f32 v164, v250, v163, v158
	v_fma_f32 v165, v251, v163, v158
	v_fma_f32 v244, v252, v163, v158
	v_fma_f32 v245, v253, v163, v158
	v_exp_f32_e32 v164, v164
	v_exp_f32_e32 v165, v165
	v_exp_f32_e32 v244, v244
	v_exp_f32_e32 v245, v245
	v_mul_f32_e32 v164, v164, v146
	v_mul_f32_e32 v165, v165, v147
	v_mul_f32_e32 v244, v244, v148
	v_mul_f32_e32 v245, v245, v149
	ds_read_b128 v[250:253], v161 offset:224
	ds_read_b128 v[146:149], v161 offset:4320
	v_mul_f32_e32 v216, v20, v164
	v_mul_f32_e32 v217, v21, v165
	v_mul_f32_e32 v218, v22, v244
	v_mul_f32_e32 v219, v23, v245
	s_waitcnt lgkmcnt(2)
	v_fma_f32 v164, v236, v163, v158
	v_fma_f32 v165, v237, v163, v158
	v_fma_f32 v244, v238, v163, v158
	v_fma_f32 v245, v239, v163, v158
	v_exp_f32_e32 v164, v164
	v_exp_f32_e32 v165, v165
	v_exp_f32_e32 v244, v244
	v_exp_f32_e32 v245, v245
	v_mul_f32_e32 v164, v164, v240
	v_mul_f32_e32 v165, v165, v241
	v_mul_f32_e32 v244, v244, v242
	v_mul_f32_e32 v245, v245, v243
	v_mul_f32_e32 v220, v24, v164
	v_mul_f32_e32 v221, v25, v165
	v_mul_f32_e32 v222, v26, v244
	v_mul_f32_e32 v223, v27, v245
	s_waitcnt lgkmcnt(0)
	v_fma_f32 v164, v250, v163, v158
	v_fma_f32 v165, v251, v163, v158
	v_fma_f32 v244, v252, v163, v158
	v_fma_f32 v245, v253, v163, v158
	v_exp_f32_e32 v164, v164
	v_exp_f32_e32 v165, v165
	v_exp_f32_e32 v244, v244
	v_exp_f32_e32 v245, v245
	v_mul_f32_e32 v164, v164, v146
	v_mul_f32_e32 v165, v165, v147
	v_mul_f32_e32 v244, v244, v148
	v_mul_f32_e32 v245, v245, v149
	v_mul_f32_e32 v224, v28, v164
	v_mul_f32_e32 v225, v29, v165
	v_mul_f32_e32 v226, v30, v244
	v_mul_f32_e32 v227, v31, v245
	s_cmp_lg_u32 s98, 1
	s_cbranch_scc1 .Lp5_nodiag1
; #define LAS __attribute__((address_space(3)))
; __device__ __forceinline__ f32x16 mfma32(bf16x8 a, bf16x8 b, f32x16 c) { return __builtin_amdgcn_mfma_f32_32x32x16_bf16(a, b, c, 0, 0, 0); }
; __device__ __forceinline__ void phase_ssd_y(const PT& p, LAS unsigned char* lds, int tid, int lane, int wave) {
;     ...
;                 if (sb <= lb) {
;                     f32x16 mm;
; #pragma unroll
;                     for (int qd = 0; qd < 4; ++qd) {
;                         const int s0 = sb * 32 + 8 * qd + 4 * h;
;                         const f32x4 as = *(const LAS f32x4*)(acum + r * 128 + s0), ds = *(const LAS f32x4*)(dtt + r * 128 + s0);
; #pragma unroll
;                         for (int j = 0; j < 4; ++j) { const float v = X[sb][4 * qd + j] * __expf(al - as[j]) * ds[j]; mm[4 * qd + j] = (s0 + j < l) ? v : ((s0 + j == l) ? v + dsk : 0.f); }
;                     }
; #pragma unroll
;                     for (int s2 = 0; s2 < 2; ++s2) acc = mfma32(ld_frag8x2(xrow + sb * 32 + 16 * s2), pack_frag(mm, s2), acc);
	v_add_f32_e32 v208, v212, v159
	v_add_f32_e32 v209, v213, v159
	v_cmp_eq_u32_e32 vcc, 0, v160
	v_cmp_eq_u32_e64 s[100:101], 1, v160
	s_nop 0
	v_cndmask_b32_e32 v208, 0, v208, vcc
	v_cndmask_b32_e64 v209, 0, v209, s[100:101]
	v_cmp_lt_i32_e32 vcc, 0, v160
	v_cmp_lt_i32_e64 s[100:101], 1, v160
	s_nop 0
	v_cndmask_b32_e32 v212, v208, v212, vcc
	v_cndmask_b32_e64 v213, v209, v213, s[100:101]
	v_add_f32_e32 v208, v214, v159
	v_add_f32_e32 v209, v215, v159
	v_cmp_eq_u32_e32 vcc, 2, v160
	v_cmp_eq_u32_e64 s[100:101], 3, v160
	s_nop 0
	v_cndmask_b32_e32 v208, 0, v208, vcc
	v_cndmask_b32_e64 v209, 0, v209, s[100:101]
	v_cmp_lt_i32_e32 vcc, 2, v160
	v_cmp_lt_i32_e64 s[100:101], 3, v160
	s_nop 0
	v_cndmask_b32_e32 v214, v208, v214, vcc
	v_cndmask_b32_e64 v215, v209, v215, s[100:101]
	v_add_f32_e32 v208, v216, v159
	v_add_f32_e32 v209, v217, v159
	v_cmp_eq_u32_e32 vcc, 8, v160
	v_cmp_eq_u32_e64 s[100:101], 9, v160
	s_nop 0
	v_cndmask_b32_e32 v208, 0, v208, vcc
	v_cndmask_b32_e64 v209, 0, v209, s[100:101]
	v_cmp_lt_i32_e32 vcc, 8, v160
	v_cmp_lt_i32_e64 s[100:101], 9, v160
	s_nop 0
	v_cndmask_b32_e32 v216, v208, v216, vcc
	v_cndmask_b32_e64 v217, v209, v217, s[100:101]
	v_add_f32_e32 v208, v218, v159
	v_add_f32_e32 v209, v219, v159
	v_cmp_eq_u32_e32 vcc, 10, v160
	v_cmp_eq_u32_e64 s[100:101], 11, v160
	s_nop 0
	v_cndmask_b32_e32 v208, 0, v208, vcc
	v_cndmask_b32_e64 v209, 0, v209, s[100:101]
	v_cmp_lt_i32_e32 vcc, 10, v160
	v_cmp_lt_i32_e64 s[100:101], 11, v160
	s_nop 0
	v_cndmask_b32_e32 v218, v208, v218, vcc
	v_cndmask_b32_e64 v219, v209, v219, s[100:101]
	v_add_f32_e32 v208, v220, v159
	v_add_f32_e32 v209, v221, v159
	v_cmp_eq_u32_e32 vcc, 16, v160
	v_cmp_eq_u32_e64 s[100:101], 17, v160
	s_nop 0
	v_cndmask_b32_e32 v208, 0, v208, vcc
	v_cndmask_b32_e64 v209, 0, v209, s[100:101]
	v_cmp_lt_i32_e32 vcc, 16, v160
	v_cmp_lt_i32_e64 s[100:101], 17, v160
	s_nop 0
	v_cndmask_b32_e32 v220, v208, v220, vcc
	v_cndmask_b32_e64 v221, v209, v221, s[100:101]
	v_add_f32_e32 v208, v222, v159
	v_add_f32_e32 v209, v223, v159
	v_cmp_eq_u32_e32 vcc, 18, v160
	v_cmp_eq_u32_e64 s[100:101], 19, v160
	s_nop 0
	v_cndmask_b32_e32 v208, 0, v208, vcc
	v_cndmask_b32_e64 v209, 0, v209, s[100:101]
	v_cmp_lt_i32_e32 vcc, 18, v160
	v_cmp_lt_i32_e64 s[100:101], 19, v160
	s_nop 0
	v_cndmask_b32_e32 v222, v208, v222, vcc
	v_cndmask_b32_e64 v223, v209, v223, s[100:101]
	v_add_f32_e32 v208, v224, v159
	v_add_f32_e32 v209, v225, v159
	v_cmp_eq_u32_e32 vcc, 24, v160
	v_cmp_eq_u32_e64 s[100:101], 25, v160
	s_nop 0
	v_cndmask_b32_e32 v208, 0, v208, vcc
	v_cndmask_b32_e64 v209, 0, v209, s[100:101]
	v_cmp_lt_i32_e32 vcc, 24, v160
	v_cmp_lt_i32_e64 s[100:101], 25, v160
	s_nop 0
	v_cndmask_b32_e32 v224, v208, v224, vcc
	v_cndmask_b32_e64 v225, v209, v225, s[100:101]
	v_add_f32_e32 v208, v226, v159
	v_add_f32_e32 v209, v227, v159
	v_cmp_eq_u32_e32 vcc, 26, v160
	v_cmp_eq_u32_e64 s[100:101], 27, v160
	s_nop 0
	v_cndmask_b32_e32 v208, 0, v208, vcc
	v_cndmask_b32_e64 v209, 0, v209, s[100:101]
	v_cmp_lt_i32_e32 vcc, 26, v160
	v_cmp_lt_i32_e64 s[100:101], 27, v160
	s_nop 0
	v_cndmask_b32_e32 v226, v208, v226, vcc
	v_cndmask_b32_e64 v227, v209, v227, s[100:101]
.Lp5_nodiag1:
	v_cvt_pk_bf16_f32 v228, v212, v213
	v_cvt_pk_bf16_f32 v229, v214, v215
	v_cvt_pk_bf16_f32 v230, v216, v217
	v_cvt_pk_bf16_f32 v231, v218, v219
	v_cvt_pk_bf16_f32 v232, v220, v221
	v_cvt_pk_bf16_f32 v233, v222, v223
	v_cvt_pk_bf16_f32 v234, v224, v225
	v_cvt_pk_bf16_f32 v235, v226, v227
	s_nop 0
	s_waitcnt vmcnt(8)
	v_mfma_f32_32x32x16_bf16 v[64:79], v[192:195], v[228:231], v[64:79]
	v_mfma_f32_32x32x16_bf16 v[64:79], v[198:201], v[232:235], v[64:79]
	s_cmp_lt_u32 s98, 2
	s_cbranch_scc1 .Lp5_gate
	ds_read_b128 v[236:239], v161 offset:256
	ds_read_b128 v[240:243], v161 offset:4352
	ds_read_b128 v[250:253], v161 offset:288
	ds_read_b128 v[146:149], v161 offset:4384
	s_waitcnt lgkmcnt(2)
	v_fma_f32 v164, v236, v163, v158
	v_fma_f32 v165, v237, v163, v158
	v_fma_f32 v244, v238, v163, v158
	v_fma_f32 v245, v239, v163, v158
	v_exp_f32_e32 v164, v164
	v_exp_f32_e32 v165, v165
	v_exp_f32_e32 v244, v244
	v_exp_f32_e32 v245, v245
	v_mul_f32_e32 v164, v164, v240
	v_mul_f32_e32 v165, v165, v241
	v_mul_f32_e32 v244, v244, v242
	v_mul_f32_e32 v245, v245, v243
	ds_read_b128 v[236:239], v161 offset:320
	ds_read_b128 v[240:243], v161 offset:4416
	v_mul_f32_e32 v212, v48, v164
	v_mul_f32_e32 v213, v49, v165
	v_mul_f32_e32 v214, v50, v244
	v_mul_f32_e32 v215, v51, v245
	s_waitcnt lgkmcnt(2)
	v_fma_f32 v164, v250, v163, v158
	v_fma_f32 v165, v251, v163, v158
	v_fma_f32 v244, v252, v163, v158
	v_fma_f32 v245, v253, v163, v158
	v_exp_f32_e32 v164, v164
	v_exp_f32_e32 v165, v165
	v_exp_f32_e32 v244, v244
	v_exp_f32_e32 v245, v245
	v_mul_f32_e32 v164, v164, v146
	v_mul_f32_e32 v165, v165, v147
	v_mul_f32_e32 v244, v244, v148
	v_mul_f32_e32 v245, v245, v149
	ds_read_b128 v[250:253], v161 offset:352
	ds_read_b128 v[146:149], v161 offset:4448
	v_mul_f32_e32 v216, v52, v164
	v_mul_f32_e32 v217, v53, v165
	v_mul_f32_e32 v218, v54, v244
	v_mul_f32_e32 v219, v55, v245
	s_waitcnt lgkmcnt(2)
	v_fma_f32 v164, v236, v163, v158
	v_fma_f32 v165, v237, v163, v158
	v_fma_f32 v244, v238, v163, v158
	v_fma_f32 v245, v239, v163, v158
	v_exp_f32_e32 v164, v164
	v_exp_f32_e32 v165, v165
	v_exp_f32_e32 v244, v244
	v_exp_f32_e32 v245, v245
	v_mul_f32_e32 v164, v164, v240
	v_mul_f32_e32 v165, v165, v241
	v_mul_f32_e32 v244, v244, v242
	v_mul_f32_e32 v245, v245, v243
	v_mul_f32_e32 v220, v56, v164
	v_mul_f32_e32 v221, v57, v165
	v_mul_f32_e32 v222, v58, v244
	v_mul_f32_e32 v223, v59, v245
	s_waitcnt lgkmcnt(0)
	v_fma_f32 v164, v250, v163, v158
	v_fma_f32 v165, v251, v163, v158
	v_fma_f32 v244, v252, v163, v158
	v_fma_f32 v245, v253, v163, v158
	v_exp_f32_e32 v164, v164
	v_exp_f32_e32 v165, v165
	v_exp_f32_e32 v244, v244
	v_exp_f32_e32 v245, v245
	v_mul_f32_e32 v164, v164, v146
	v_mul_f32_e32 v165, v165, v147
	v_mul_f32_e32 v244, v244, v148
	v_mul_f32_e32 v245, v245, v149
	v_mul_f32_e32 v224, v60, v164
	v_mul_f32_e32 v225, v61, v165
	v_mul_f32_e32 v226, v62, v244
	v_mul_f32_e32 v227, v63, v245
	s_cmp_lg_u32 s98, 2
	s_cbranch_scc1 .Lp5_nodiag2
; #define LAS __attribute__((address_space(3)))
; __device__ __forceinline__ f32x16 mfma32(bf16x8 a, bf16x8 b, f32x16 c) { return __builtin_amdgcn_mfma_f32_32x32x16_bf16(a, b, c, 0, 0, 0); }
; __device__ __forceinline__ void phase_ssd_y(const PT& p, LAS unsigned char* lds, int tid, int lane, int wave) {
;     ...
;                 if (sb <= lb) {
;                     f32x16 mm;
; #pragma unroll
;                     for (int qd = 0; qd < 4; ++qd) {
;                         const int s0 = sb * 32 + 8 * qd + 4 * h;
;                         const f32x4 as = *(const LAS f32x4*)(acum + r * 128 + s0), ds = *(const LAS f32x4*)(dtt + r * 128 + s0);
; #pragma unroll
;                         for (int j = 0; j < 4; ++j) { const float v = X[sb][4 * qd + j] * __expf(al - as[j]) * ds[j]; mm[4 * qd + j] = (s0 + j < l) ? v : ((s0 + j == l) ? v + dsk : 0.f); }
;                     }
; #pragma unroll
;                     for (int s2 = 0; s2 < 2; ++s2) acc = mfma32(ld_frag8x2(xrow + sb * 32 + 16 * s2), pack_frag(mm, s2), acc);
	v_add_f32_e32 v208, v212, v159
	v_add_f32_e32 v209, v213, v159
	v_cmp_eq_u32_e32 vcc, 0, v160
	v_cmp_eq_u32_e64 s[100:101], 1, v160
	s_nop 0
	v_cndmask_b32_e32 v208, 0, v208, vcc
	v_cndmask_b32_e64 v209, 0, v209, s[100:101]
	v_cmp_lt_i32_e32 vcc, 0, v160
	v_cmp_lt_i32_e64 s[100:101], 1, v160
	s_nop 0
	v_cndmask_b32_e32 v212, v208, v212, vcc
	v_cndmask_b32_e64 v213, v209, v213, s[100:101]
	v_add_f32_e32 v208, v214, v159
	v_add_f32_e32 v209, v215, v159
	v_cmp_eq_u32_e32 vcc, 2, v160
	v_cmp_eq_u32_e64 s[100:101], 3, v160
	s_nop 0
	v_cndmask_b32_e32 v208, 0, v208, vcc
	v_cndmask_b32_e64 v209, 0, v209, s[100:101]
	v_cmp_lt_i32_e32 vcc, 2, v160
	v_cmp_lt_i32_e64 s[100:101], 3, v160
	s_nop 0
	v_cndmask_b32_e32 v214, v208, v214, vcc
	v_cndmask_b32_e64 v215, v209, v215, s[100:101]
	v_add_f32_e32 v208, v216, v159
	v_add_f32_e32 v209, v217, v159
	v_cmp_eq_u32_e32 vcc, 8, v160
	v_cmp_eq_u32_e64 s[100:101], 9, v160
	s_nop 0
	v_cndmask_b32_e32 v208, 0, v208, vcc
	v_cndmask_b32_e64 v209, 0, v209, s[100:101]
	v_cmp_lt_i32_e32 vcc, 8, v160
	v_cmp_lt_i32_e64 s[100:101], 9, v160
	s_nop 0
	v_cndmask_b32_e32 v216, v208, v216, vcc
	v_cndmask_b32_e64 v217, v209, v217, s[100:101]
	v_add_f32_e32 v208, v218, v159
	v_add_f32_e32 v209, v219, v159
	v_cmp_eq_u32_e32 vcc, 10, v160
	v_cmp_eq_u32_e64 s[100:101], 11, v160
	s_nop 0
	v_cndmask_b32_e32 v208, 0, v208, vcc
	v_cndmask_b32_e64 v209, 0, v209, s[100:101]
	v_cmp_lt_i32_e32 vcc, 10, v160
	v_cmp_lt_i32_e64 s[100:101], 11, v160
	s_nop 0
	v_cndmask_b32_e32 v218, v208, v218, vcc
	v_cndmask_b32_e64 v219, v209, v219, s[100:101]
	v_add_f32_e32 v208, v220, v159
	v_add_f32_e32 v209, v221, v159
	v_cmp_eq_u32_e32 vcc, 16, v160
	v_cmp_eq_u32_e64 s[100:101], 17, v160
	s_nop 0
	v_cndmask_b32_e32 v208, 0, v208, vcc
	v_cndmask_b32_e64 v209, 0, v209, s[100:101]
	v_cmp_lt_i32_e32 vcc, 16, v160
	v_cmp_lt_i32_e64 s[100:101], 17, v160
	s_nop 0
	v_cndmask_b32_e32 v220, v208, v220, vcc
	v_cndmask_b32_e64 v221, v209, v221, s[100:101]
	v_add_f32_e32 v208, v222, v159
	v_add_f32_e32 v209, v223, v159
	v_cmp_eq_u32_e32 vcc, 18, v160
	v_cmp_eq_u32_e64 s[100:101], 19, v160
	s_nop 0
	v_cndmask_b32_e32 v208, 0, v208, vcc
	v_cndmask_b32_e64 v209, 0, v209, s[100:101]
	v_cmp_lt_i32_e32 vcc, 18, v160
	v_cmp_lt_i32_e64 s[100:101], 19, v160
	s_nop 0
	v_cndmask_b32_e32 v222, v208, v222, vcc
	v_cndmask_b32_e64 v223, v209, v223, s[100:101]
	v_add_f32_e32 v208, v224, v159
	v_add_f32_e32 v209, v225, v159
	v_cmp_eq_u32_e32 vcc, 24, v160
	v_cmp_eq_u32_e64 s[100:101], 25, v160
	s_nop 0
	v_cndmask_b32_e32 v208, 0, v208, vcc
	v_cndmask_b32_e64 v209, 0, v209, s[100:101]
	v_cmp_lt_i32_e32 vcc, 24, v160
	v_cmp_lt_i32_e64 s[100:101], 25, v160
	s_nop 0
	v_cndmask_b32_e32 v224, v208, v224, vcc
	v_cndmask_b32_e64 v225, v209, v225, s[100:101]
	v_add_f32_e32 v208, v226, v159
	v_add_f32_e32 v209, v227, v159
	v_cmp_eq_u32_e32 vcc, 26, v160
	v_cmp_eq_u32_e64 s[100:101], 27, v160
	s_nop 0
	v_cndmask_b32_e32 v208, 0, v208, vcc
	v_cndmask_b32_e64 v209, 0, v209, s[100:101]
	v_cmp_lt_i32_e32 vcc, 26, v160
	v_cmp_lt_i32_e64 s[100:101], 27, v160
	s_nop 0
	v_cndmask_b32_e32 v226, v208, v226, vcc
	v_cndmask_b32_e64 v227, v209, v227, s[100:101]
.Lp5_nodiag2:
	v_cvt_pk_bf16_f32 v228, v212, v213
	v_cvt_pk_bf16_f32 v229, v214, v215
	v_cvt_pk_bf16_f32 v230, v216, v217
	v_cvt_pk_bf16_f32 v231, v218, v219
	v_cvt_pk_bf16_f32 v232, v220, v221
	v_cvt_pk_bf16_f32 v233, v222, v223
	v_cvt_pk_bf16_f32 v234, v224, v225
	v_cvt_pk_bf16_f32 v235, v226, v227
	s_nop 0
	s_waitcnt vmcnt(4)
	v_mfma_f32_32x32x16_bf16 v[64:79], v[112:115], v[228:231], v[64:79]
	v_mfma_f32_32x32x16_bf16 v[64:79], v[202:205], v[232:235], v[64:79]
	s_cmp_lt_u32 s98, 3
	s_cbranch_scc1 .Lp5_gate
	ds_read_b128 v[236:239], v161 offset:384
	ds_read_b128 v[240:243], v161 offset:4480
	ds_read_b128 v[250:253], v161 offset:416
	ds_read_b128 v[146:149], v161 offset:4512
	s_waitcnt lgkmcnt(2)
	v_fma_f32 v164, v236, v163, v158
	v_fma_f32 v165, v237, v163, v158
	v_fma_f32 v244, v238, v163, v158
	v_fma_f32 v245, v239, v163, v158
	v_exp_f32_e32 v164, v164
	v_exp_f32_e32 v165, v165
	v_exp_f32_e32 v244, v244
	v_exp_f32_e32 v245, v245
	v_mul_f32_e32 v164, v164, v240
	v_mul_f32_e32 v165, v165, v241
	v_mul_f32_e32 v244, v244, v242
	v_mul_f32_e32 v245, v245, v243
	ds_read_b128 v[236:239], v161 offset:448
	ds_read_b128 v[240:243], v161 offset:4544
	v_mul_f32_e32 v212, v32, v164
	v_mul_f32_e32 v213, v33, v165
	v_mul_f32_e32 v214, v34, v244
	v_mul_f32_e32 v215, v35, v245
	s_waitcnt lgkmcnt(2)
	v_fma_f32 v164, v250, v163, v158
	v_fma_f32 v165, v251, v163, v158
	v_fma_f32 v244, v252, v163, v158
	v_fma_f32 v245, v253, v163, v158
	v_exp_f32_e32 v164, v164
	v_exp_f32_e32 v165, v165
	v_exp_f32_e32 v244, v244
	v_exp_f32_e32 v245, v245
	v_mul_f32_e32 v164, v164, v146
	v_mul_f32_e32 v165, v165, v147
	v_mul_f32_e32 v244, v244, v148
	v_mul_f32_e32 v245, v245, v149
	ds_read_b128 v[250:253], v161 offset:480
	ds_read_b128 v[146:149], v161 offset:4576
	v_mul_f32_e32 v216, v36, v164
	v_mul_f32_e32 v217, v37, v165
	v_mul_f32_e32 v218, v38, v244
	v_mul_f32_e32 v219, v39, v245
	s_waitcnt lgkmcnt(2)
	v_fma_f32 v164, v236, v163, v158
	v_fma_f32 v165, v237, v163, v158
	v_fma_f32 v244, v238, v163, v158
	v_fma_f32 v245, v239, v163, v158
	v_exp_f32_e32 v164, v164
	v_exp_f32_e32 v165, v165
	v_exp_f32_e32 v244, v244
	v_exp_f32_e32 v245, v245
	v_mul_f32_e32 v164, v164, v240
	v_mul_f32_e32 v165, v165, v241
	v_mul_f32_e32 v244, v244, v242
	v_mul_f32_e32 v245, v245, v243
	v_mul_f32_e32 v220, v40, v164
	v_mul_f32_e32 v221, v41, v165
	v_mul_f32_e32 v222, v42, v244
	v_mul_f32_e32 v223, v43, v245
	s_waitcnt lgkmcnt(0)
	v_fma_f32 v164, v250, v163, v158
	v_fma_f32 v165, v251, v163, v158
	v_fma_f32 v244, v252, v163, v158
	v_fma_f32 v245, v253, v163, v158
	v_exp_f32_e32 v164, v164
	v_exp_f32_e32 v165, v165
	v_exp_f32_e32 v244, v244
	v_exp_f32_e32 v245, v245
	v_mul_f32_e32 v164, v164, v146
	v_mul_f32_e32 v165, v165, v147
	v_mul_f32_e32 v244, v244, v148
	v_mul_f32_e32 v245, v245, v149
	v_mul_f32_e32 v224, v44, v164
	v_mul_f32_e32 v225, v45, v165
	v_mul_f32_e32 v226, v46, v244
	v_mul_f32_e32 v227, v47, v245
	s_cmp_lg_u32 s98, 3
	s_cbranch_scc1 .Lp5_nodiag3
; #define LAS __attribute__((address_space(3)))
; __device__ __forceinline__ float bflo(unsigned u) { return __uint_as_float(u << 16); }
; __device__ __forceinline__ float bfhi(unsigned u) { return __uint_as_float(u & 0xffff0000u); }
; __device__ __forceinline__ f32x16 mfma32(bf16x8 a, bf16x8 b, f32x16 c) { return __builtin_amdgcn_mfma_f32_32x32x16_bf16(a, b, c, 0, 0, 0); }
; __device__ __forceinline__ void phase_ssd_y(const PT& p, LAS unsigned char* lds, int tid, int lane, int wave) {
;     ...
; #pragma unroll
;                     for (int s2 = 0; s2 < 2; ++s2) acc = mfma32(ld_frag8x2(xrow + sb * 32 + 16 * s2), pack_frag(mm, s2), acc);
;                 }
;             }
; #pragma unroll
;             for (int qd = 0; qd < 4; ++qd) {
;                 LAS u32x2* yp = (LAS u32x2*)(tile + l * SY_TP + (r * 64 + pb * 32 + 8 * qd + 4 * h) * 2); const u32x2 zz = *yp;
;                 const float y0 = acc[4 * qd] * bflo(zz.x), y1 = acc[4 * qd + 1] * bfhi(zz.x);
;                 const float y2 = acc[4 * qd + 2] * bflo(zz.y), y3 = acc[4 * qd + 3] * bfhi(zz.y);
;                 ssq += (y0 * y0 + y1 * y1) + (y2 * y2 + y3 * y3);
;                 u32x2 w; w.x = pk2(y0, y1); w.y = pk2(y2, y3); *yp = w;
;             }
;         }
	v_add_f32_e32 v208, v212, v159
	v_add_f32_e32 v209, v213, v159
	v_cmp_eq_u32_e32 vcc, 0, v160
	v_cmp_eq_u32_e64 s[100:101], 1, v160
	s_nop 0
	v_cndmask_b32_e32 v208, 0, v208, vcc
	v_cndmask_b32_e64 v209, 0, v209, s[100:101]
	v_cmp_lt_i32_e32 vcc, 0, v160
	v_cmp_lt_i32_e64 s[100:101], 1, v160
	s_nop 0
	v_cndmask_b32_e32 v212, v208, v212, vcc
	v_cndmask_b32_e64 v213, v209, v213, s[100:101]
	v_add_f32_e32 v208, v214, v159
	v_add_f32_e32 v209, v215, v159
	v_cmp_eq_u32_e32 vcc, 2, v160
	v_cmp_eq_u32_e64 s[100:101], 3, v160
	s_nop 0
	v_cndmask_b32_e32 v208, 0, v208, vcc
	v_cndmask_b32_e64 v209, 0, v209, s[100:101]
	v_cmp_lt_i32_e32 vcc, 2, v160
	v_cmp_lt_i32_e64 s[100:101], 3, v160
	s_nop 0
	v_cndmask_b32_e32 v214, v208, v214, vcc
	v_cndmask_b32_e64 v215, v209, v215, s[100:101]
	v_add_f32_e32 v208, v216, v159
	v_add_f32_e32 v209, v217, v159
	v_cmp_eq_u32_e32 vcc, 8, v160
	v_cmp_eq_u32_e64 s[100:101], 9, v160
	s_nop 0
	v_cndmask_b32_e32 v208, 0, v208, vcc
	v_cndmask_b32_e64 v209, 0, v209, s[100:101]
	v_cmp_lt_i32_e32 vcc, 8, v160
	v_cmp_lt_i32_e64 s[100:101], 9, v160
	s_nop 0
	v_cndmask_b32_e32 v216, v208, v216, vcc
	v_cndmask_b32_e64 v217, v209, v217, s[100:101]
	v_add_f32_e32 v208, v218, v159
	v_add_f32_e32 v209, v219, v159
	v_cmp_eq_u32_e32 vcc, 10, v160
	v_cmp_eq_u32_e64 s[100:101], 11, v160
	s_nop 0
	v_cndmask_b32_e32 v208, 0, v208, vcc
	v_cndmask_b32_e64 v209, 0, v209, s[100:101]
	v_cmp_lt_i32_e32 vcc, 10, v160
	v_cmp_lt_i32_e64 s[100:101], 11, v160
	s_nop 0
	v_cndmask_b32_e32 v218, v208, v218, vcc
	v_cndmask_b32_e64 v219, v209, v219, s[100:101]
	v_add_f32_e32 v208, v220, v159
	v_add_f32_e32 v209, v221, v159
	v_cmp_eq_u32_e32 vcc, 16, v160
	v_cmp_eq_u32_e64 s[100:101], 17, v160
	s_nop 0
	v_cndmask_b32_e32 v208, 0, v208, vcc
	v_cndmask_b32_e64 v209, 0, v209, s[100:101]
	v_cmp_lt_i32_e32 vcc, 16, v160
	v_cmp_lt_i32_e64 s[100:101], 17, v160
	s_nop 0
	v_cndmask_b32_e32 v220, v208, v220, vcc
	v_cndmask_b32_e64 v221, v209, v221, s[100:101]
	v_add_f32_e32 v208, v222, v159
	v_add_f32_e32 v209, v223, v159
	v_cmp_eq_u32_e32 vcc, 18, v160
	v_cmp_eq_u32_e64 s[100:101], 19, v160
	s_nop 0
	v_cndmask_b32_e32 v208, 0, v208, vcc
	v_cndmask_b32_e64 v209, 0, v209, s[100:101]
	v_cmp_lt_i32_e32 vcc, 18, v160
	v_cmp_lt_i32_e64 s[100:101], 19, v160
	s_nop 0
	v_cndmask_b32_e32 v222, v208, v222, vcc
	v_cndmask_b32_e64 v223, v209, v223, s[100:101]
	v_add_f32_e32 v208, v224, v159
	v_add_f32_e32 v209, v225, v159
	v_cmp_eq_u32_e32 vcc, 24, v160
	v_cmp_eq_u32_e64 s[100:101], 25, v160
	s_nop 0
	v_cndmask_b32_e32 v208, 0, v208, vcc
	v_cndmask_b32_e64 v209, 0, v209, s[100:101]
	v_cmp_lt_i32_e32 vcc, 24, v160
	v_cmp_lt_i32_e64 s[100:101], 25, v160
	s_nop 0
	v_cndmask_b32_e32 v224, v208, v224, vcc
	v_cndmask_b32_e64 v225, v209, v225, s[100:101]
	v_add_f32_e32 v208, v226, v159
	v_add_f32_e32 v209, v227, v159
	v_cmp_eq_u32_e32 vcc, 26, v160
	v_cmp_eq_u32_e64 s[100:101], 27, v160
	s_nop 0
	v_cndmask_b32_e32 v208, 0, v208, vcc
	v_cndmask_b32_e64 v209, 0, v209, s[100:101]
	v_cmp_lt_i32_e32 vcc, 26, v160
	v_cmp_lt_i32_e64 s[100:101], 27, v160
	s_nop 0
	v_cndmask_b32_e32 v226, v208, v226, vcc
	v_cndmask_b32_e64 v227, v209, v227, s[100:101]
.Lp5_nodiag3:
	v_cvt_pk_bf16_f32 v228, v212, v213
	v_cvt_pk_bf16_f32 v229, v214, v215
	v_cvt_pk_bf16_f32 v230, v216, v217
	v_cvt_pk_bf16_f32 v231, v218, v219
	v_cvt_pk_bf16_f32 v232, v220, v221
	v_cvt_pk_bf16_f32 v233, v222, v223
	v_cvt_pk_bf16_f32 v234, v224, v225
	v_cvt_pk_bf16_f32 v235, v226, v227
	s_nop 0
	s_waitcnt vmcnt(0)
	v_mfma_f32_32x32x16_bf16 v[64:79], v[150:153], v[228:231], v[64:79]
	v_mfma_f32_32x32x16_bf16 v[64:79], v[154:157], v[232:235], v[64:79]
.Lp5_gate:
	s_waitcnt vmcnt(0)
	s_nop 10
	ds_read_b64 v[202:203], v162 offset:0
	s_waitcnt lgkmcnt(0)
	v_lshlrev_b32_e32 v208, 16, v202
	v_and_b32_e32 v209, 0xffff0000, v202
	v_lshlrev_b32_e32 v254, 16, v203
	v_and_b32_e32 v255, 0xffff0000, v203
	v_mul_f32_e32 v208, v64, v208
	v_mul_f32_e32 v209, v65, v209
	v_mul_f32_e32 v254, v66, v254
	v_mul_f32_e32 v255, v67, v255
	v_mul_f32_e32 v164, v208, v208
	v_mul_f32_e32 v165, v254, v254
	v_fmac_f32_e32 v164, v209, v209
	v_fmac_f32_e32 v165, v255, v255
	v_cvt_pk_bf16_f32 v202, v208, v209
	v_cvt_pk_bf16_f32 v203, v254, v255
	v_add_f32_e32 v164, v164, v165
	ds_write_b64 v162, v[202:203] offset:0
	v_add_f32_e32 v210, v210, v164
	ds_read_b64 v[202:203], v162 offset:16
	s_waitcnt lgkmcnt(0)
	v_lshlrev_b32_e32 v208, 16, v202
	v_and_b32_e32 v209, 0xffff0000, v202
	v_lshlrev_b32_e32 v254, 16, v203
	v_and_b32_e32 v255, 0xffff0000, v203
	v_mul_f32_e32 v208, v68, v208
	v_mul_f32_e32 v209, v69, v209
	v_mul_f32_e32 v254, v70, v254
	v_mul_f32_e32 v255, v71, v255
	v_mul_f32_e32 v164, v208, v208
	v_mul_f32_e32 v165, v254, v254
	v_fmac_f32_e32 v164, v209, v209
	v_fmac_f32_e32 v165, v255, v255
	v_cvt_pk_bf16_f32 v202, v208, v209
	v_cvt_pk_bf16_f32 v203, v254, v255
	v_add_f32_e32 v164, v164, v165
	ds_write_b64 v162, v[202:203] offset:16
	v_add_f32_e32 v210, v210, v164
	ds_read_b64 v[202:203], v162 offset:32
	s_waitcnt lgkmcnt(0)
	v_lshlrev_b32_e32 v208, 16, v202
	v_and_b32_e32 v209, 0xffff0000, v202
	v_lshlrev_b32_e32 v254, 16, v203
	v_and_b32_e32 v255, 0xffff0000, v203
	v_mul_f32_e32 v208, v72, v208
	v_mul_f32_e32 v209, v73, v209
	v_mul_f32_e32 v254, v74, v254
	v_mul_f32_e32 v255, v75, v255
	v_mul_f32_e32 v164, v208, v208
	v_mul_f32_e32 v165, v254, v254
	v_fmac_f32_e32 v164, v209, v209
	v_fmac_f32_e32 v165, v255, v255
	v_cvt_pk_bf16_f32 v202, v208, v209
	v_cvt_pk_bf16_f32 v203, v254, v255
	v_add_f32_e32 v164, v164, v165
	ds_write_b64 v162, v[202:203] offset:32
	v_add_f32_e32 v210, v210, v164
	ds_read_b64 v[202:203], v162 offset:48
	s_waitcnt lgkmcnt(0)
	v_lshlrev_b32_e32 v208, 16, v202
	v_and_b32_e32 v209, 0xffff0000, v202
	v_lshlrev_b32_e32 v254, 16, v203
	v_and_b32_e32 v255, 0xffff0000, v203
	v_mul_f32_e32 v208, v76, v208
	v_mul_f32_e32 v209, v77, v209
	v_mul_f32_e32 v254, v78, v254
	v_mul_f32_e32 v255, v79, v255
	v_mul_f32_e32 v164, v208, v208
	v_mul_f32_e32 v165, v254, v254
	v_fmac_f32_e32 v164, v209, v209
	v_fmac_f32_e32 v165, v255, v255
	v_cvt_pk_bf16_f32 v202, v208, v209
	v_cvt_pk_bf16_f32 v203, v254, v255
	v_add_f32_e32 v164, v164, v165
	ds_write_b64 v162, v[202:203] offset:48
	v_add_f32_e32 v210, v210, v164
	v_add_u32_e32 v161, 0x200, v161
	v_add_u32_e32 v141, 0x200, v141
	v_add_u32_e32 v162, 0x80, v162
	s_add_u32 s84, s84, 4
	s_addc_u32 s85, s85, 0
	s_add_u32 s94, s94, 0x4000
	s_cmp_eq_u32 s94, 0x20000
	s_cbranch_scc0 .Lp5_head
	s_waitcnt lgkmcnt(0)
